# gate/up epilogue hit path: the 8 stashed rstd factors fetched with two ds_read_b128 up front (one wait) instead of 8 ds_read_b32 each followed by a wait
# speedup vs baseline: 1.0059x; 1.0038x over previous
; __device__ __forceinline__ unsigned pk_bf16(float lo, float hi) { f32x2e v = {lo, hi}; bf16x2e b = __builtin_convertvector(v, bf16x2e); return __builtin_bit_cast(unsigned, b); }
; __device__ __forceinline__ float silu_mul(float g, float u) { return g * __builtin_amdgcn_rcpf(1.0f + __builtin_amdgcn_exp2f(-1.4426950408889634f * g)) * u; }
;     __device__ __forceinline__ void operator()(const f32x4 (&acc)[2][2][4][2], const Unit& u, int wr, int wc, int fr, int fq) const {
;         const int row0 = u.pm * BM + wr * 64 + fr; const int col0 = u.pn * HALF + wc * 32 + 8 * fq;
;         float rsa[2][4]; tile_rstd(rsa, ss, u.pm * BM, wr, fr, fq);
; #pragma unroll
;         for (int ai = 0; ai < 2; ++ai)
; #pragma unroll
;             for (int m = 0; m < 4; ++m) { bf16_t* rowp = O + (size_t)(row0 + ai * HALF + m * 16) * ldc + col0;
;                 const float rs = rsa[ai][m];
;                 const f32x4 g0 = acc[ai][0][m][0] * rs, g1 = acc[ai][0][m][1] * rs, u0 = acc[ai][1][m][0] * rs, u1 = acc[ai][1][m][1] * rs;
;                 u32x4 w; w.x = pk_bf16(silu_mul(g0[0], u0[0]), silu_mul(g0[1], u0[1])); w.y = pk_bf16(silu_mul(g0[2], u0[2]), silu_mul(g0[3], u0[3]));
;                 w.z = pk_bf16(silu_mul(g1[0], u1[0]), silu_mul(g1[1], u1[1])); w.w = pk_bf16(silu_mul(g1[2], u1[2]), silu_mul(g1[3], u1[3]));
;                 *(u32x4*)rowp = w; }
.Lswi_hit:
	v_lshrrev_b32_e32 v236, 6, v216
	v_and_b32_e32 v237, 15, v216
	v_lshlrev_b32_e32 v236, 9, v236
	v_lshl_add_u32 v236, v237, 5, v236
	v_add_u32_e32 v236, 0x21000, v236
	ds_read_b128 v[152:155], v236
	ds_read_b128 v[156:159], v236 offset:16
	v_mov_b32_e32 v237, s6
	v_add_u32_e32 v237, 1, v237
	s_lshl_b32 s0, s6, 8
	s_add_i32 s0, s0, s73
	v_or_b32_e32 v130, s0, v206
	v_add_u32_e32 v130, 0xb0, v130
	v_ashrrev_i32_e32 v131, 31, v130
	v_lshlrev_b64 v[130:131], 7, v[130:131]
	v_lshl_add_u64 v[130:131], v[184:185], 0, v[130:131]
	s_nop 0
	v_and_b32_e32 v192, 64, v220
	v_xor_b32_e32 v191, 1, v220
	v_add_u32_e32 v192, 64, v192
	v_cmp_lt_i32_e32 vcc, v191, v192
	v_or_b32_e32 v210, s0, v193
	v_readlane_b32 s0, v254, 63
	v_cndmask_b32_e32 v191, v220, v191, vcc
	v_lshlrev_b32_e32 v212, 2, v191
	v_xor_b32_e32 v191, 2, v220
	v_cmp_lt_i32_e32 vcc, v191, v192
	v_lshl_or_b32 v190, s2, 7, v208
	v_readlane_b32 s1, v255, 0
	v_cndmask_b32_e32 v191, v220, v191, vcc
	v_lshlrev_b32_e32 v211, 2, v191
	s_movk_i32 s2, 0x2c00
	s_waitcnt vmcnt(0) lgkmcnt(0)
	s_nop 0
	s_nop 0
	s_waitcnt lgkmcnt(0)
	s_waitcnt lgkmcnt(0)
	v_mov_b64_e32 v[204:205], s[24:25]
	s_nop 0
	s_nop 0
	v_mov_b32_e32 v202, v152
	s_waitcnt lgkmcnt(0)
	v_pk_mul_f32 v[126:127], v[126:127], v[202:203] op_sel_hi:[1,0]
	v_pk_mul_f32 v[118:119], v[118:119], v[202:203] op_sel_hi:[1,0]
	v_pk_mul_f32 v[140:141], v[116:117], v[202:203] op_sel_hi:[1,0]
	v_pk_mul_f32 v[116:117], v[114:115], v[202:203] op_sel_hi:[1,0]
	v_mul_f32_e32 v114, 0xbfb8aa3b, v126
	v_mul_f32_e32 v115, 0xbfb8aa3b, v127
	v_exp_f32_e32 v114, v114
	v_exp_f32_e32 v115, v115
	v_pk_mul_f32 v[128:129], v[128:129], v[202:203] op_sel_hi:[1,0]
	v_add_f32_e32 v114, 1.0, v114
	v_add_f32_e32 v115, 1.0, v115
	v_rcp_f32_e32 v114, v114
	v_rcp_f32_e32 v115, v115
	s_nop 0
	v_pk_mul_f32 v[114:115], v[126:127], v[114:115]
	v_pk_mul_f32 v[114:115], v[118:119], v[114:115]
	v_cvt_pk_bf16_f32 v114, v114, v115
	v_mul_f32_e32 v115, 0xbfb8aa3b, v128
	v_exp_f32_e32 v115, v115
	s_nop 0
	v_add_f32_e32 v115, 1.0, v115
	v_rcp_f32_e32 v118, v115
	v_mul_f32_e32 v115, 0xbfb8aa3b, v129
	v_exp_f32_e32 v115, v115
	s_waitcnt lgkmcnt(0)
	v_add_f32_e32 v115, 1.0, v115
	v_rcp_f32_e32 v119, v115
	s_waitcnt lgkmcnt(0)
	s_waitcnt lgkmcnt(0)
	v_pk_mul_f32 v[120:121], v[120:121], v[202:203] op_sel_hi:[1,0]
	v_pk_mul_f32 v[118:119], v[128:129], v[118:119]
	v_pk_mul_f32 v[122:123], v[122:123], v[202:203] op_sel_hi:[1,0]
	v_pk_mul_f32 v[118:119], v[120:121], v[118:119]
	v_cvt_pk_bf16_f32 v115, v118, v119
	v_mul_f32_e32 v118, 0xbfb8aa3b, v122
	v_mul_f32_e32 v119, 0xbfb8aa3b, v123
	v_exp_f32_e32 v118, v118
	v_exp_f32_e32 v119, v119
	s_waitcnt lgkmcnt(0)
	s_waitcnt lgkmcnt(0)
	v_add_f32_e32 v118, 1.0, v118
	v_add_f32_e32 v119, 1.0, v119
	v_mov_b32_e32 v164, v153
	v_rcp_f32_e32 v118, v118
	v_rcp_f32_e32 v119, v119
	s_waitcnt lgkmcnt(0)
	v_pk_mul_f32 v[118:119], v[122:123], v[118:119]
	v_pk_mul_f32 v[124:125], v[124:125], v[202:203] op_sel_hi:[1,0]
	v_pk_mul_f32 v[116:117], v[116:117], v[118:119]
	v_cvt_pk_bf16_f32 v116, v116, v117
	v_mul_f32_e32 v117, 0xbfb8aa3b, v124
	v_mov_b32_e32 v148, v154
	v_exp_f32_e32 v117, v117
	s_nop 0
	v_add_f32_e32 v117, 1.0, v117
	v_rcp_f32_e32 v118, v117
	v_mul_f32_e32 v117, 0xbfb8aa3b, v125
	v_exp_f32_e32 v117, v117
	v_mov_b32_e32 v136, v155
	v_add_f32_e32 v117, 1.0, v117
	v_rcp_f32_e32 v119, v117
	v_mov_b32_e32 v192, v156
	v_mov_b32_e32 v162, v157
	v_mov_b32_e32 v146, v158
	v_mov_b32_e32 v130, v159
	v_ashrrev_i32_e32 v191, 31, v190
	v_mov_b64_e32 v[132:133], s[0:1]
	v_pk_mul_f32 v[118:119], v[124:125], v[118:119]
	v_mad_i64_i32 v[138:139], s[0:1], v210, s2, v[132:133]
	v_lshlrev_b64 v[134:135], 1, v[190:191]
	v_pk_mul_f32 v[118:119], v[140:141], v[118:119]
	v_lshl_add_u64 v[138:139], v[138:139], 0, v[134:135]
	v_cvt_pk_bf16_f32 v117, v118, v119
	s_waitcnt lgkmcnt(0)
	v_pk_mul_f32 v[110:111], v[110:111], v[192:193] op_sel_hi:[1,0]
	global_store_dwordx4 v[138:139], v[114:117], off
	v_pk_mul_f32 v[102:103], v[102:103], v[192:193] op_sel_hi:[1,0]
	v_pk_mul_f32 v[112:113], v[112:113], v[192:193] op_sel_hi:[1,0]
	v_pk_mul_f32 v[116:117], v[100:101], v[192:193] op_sel_hi:[1,0]
	v_pk_mul_f32 v[100:101], v[98:99], v[192:193] op_sel_hi:[1,0]
	v_mul_f32_e32 v98, 0xbfb8aa3b, v110
	v_mul_f32_e32 v99, 0xbfb8aa3b, v111
	v_exp_f32_e32 v98, v98
	v_exp_f32_e32 v99, v99
	v_pk_mul_f32 v[104:105], v[104:105], v[192:193] op_sel_hi:[1,0]
	v_pk_mul_f32 v[106:107], v[106:107], v[192:193] op_sel_hi:[1,0]
	v_add_f32_e32 v98, 1.0, v98
	v_add_f32_e32 v99, 1.0, v99
	v_rcp_f32_e32 v98, v98
	v_rcp_f32_e32 v99, v99
	v_pk_mul_f32 v[108:109], v[108:109], v[192:193] op_sel_hi:[1,0]
	v_or_b32_e32 v114, 16, v210
	v_mad_i64_i32 v[114:115], s[0:1], v114, s2, v[132:133]
	v_pk_mul_f32 v[98:99], v[110:111], v[98:99]
	v_lshl_add_u64 v[114:115], v[114:115], 0, v[134:135]
	v_pk_mul_f32 v[98:99], v[102:103], v[98:99]
	v_pk_mul_f32 v[92:93], v[92:93], v[164:165] op_sel_hi:[1,0]
	v_cvt_pk_bf16_f32 v98, v98, v99
	v_mul_f32_e32 v99, 0xbfb8aa3b, v112
	v_exp_f32_e32 v99, v99
	v_pk_mul_f32 v[84:85], v[84:85], v[164:165] op_sel_hi:[1,0]
	v_pk_mul_f32 v[94:95], v[94:95], v[164:165] op_sel_hi:[1,0]
	v_pk_mul_f32 v[86:87], v[86:87], v[164:165] op_sel_hi:[1,0]
	v_add_f32_e32 v99, 1.0, v99
	v_rcp_f32_e32 v102, v99
	v_mul_f32_e32 v99, 0xbfb8aa3b, v113
	v_exp_f32_e32 v99, v99
	v_pk_mul_f32 v[88:89], v[88:89], v[164:165] op_sel_hi:[1,0]
	v_pk_mul_f32 v[90:91], v[90:91], v[164:165] op_sel_hi:[1,0]
	s_waitcnt lgkmcnt(0)
; __device__ __forceinline__ unsigned pk_bf16(float lo, float hi) { f32x2e v = {lo, hi}; bf16x2e b = __builtin_convertvector(v, bf16x2e); return __builtin_bit_cast(unsigned, b); }
; __device__ __forceinline__ float silu_mul(float g, float u) { return g * __builtin_amdgcn_rcpf(1.0f + __builtin_amdgcn_exp2f(-1.4426950408889634f * g)) * u; }
;     __device__ __forceinline__ void operator()(const f32x4 (&acc)[2][2][4][2], const Unit& u, int wr, int wc, int fr, int fq) const {
;     ...
;             for (int m = 0; m < 4; ++m) { bf16_t* rowp = O + (size_t)(row0 + ai * HALF + m * 16) * ldc + col0;
;                 const float rs = rsa[ai][m];
;                 const f32x4 g0 = acc[ai][0][m][0] * rs, g1 = acc[ai][0][m][1] * rs, u0 = acc[ai][1][m][0] * rs, u1 = acc[ai][1][m][1] * rs;
;                 u32x4 w; w.x = pk_bf16(silu_mul(g0[0], u0[0]), silu_mul(g0[1], u0[1])); w.y = pk_bf16(silu_mul(g0[2], u0[2]), silu_mul(g0[3], u0[3]));
;                 w.z = pk_bf16(silu_mul(g1[0], u1[0]), silu_mul(g1[1], u1[1])); w.w = pk_bf16(silu_mul(g1[2], u1[2]), silu_mul(g1[3], u1[3]));
;                 *(u32x4*)rowp = w; }
	v_pk_mul_f32 v[76:77], v[76:77], v[162:163] op_sel_hi:[1,0]
	v_add_f32_e32 v99, 1.0, v99
	v_rcp_f32_e32 v103, v99
	v_pk_mul_f32 v[68:69], v[68:69], v[162:163] op_sel_hi:[1,0]
	v_pk_mul_f32 v[78:79], v[78:79], v[162:163] op_sel_hi:[1,0]
	v_pk_mul_f32 v[70:71], v[70:71], v[162:163] op_sel_hi:[1,0]
	v_pk_mul_f32 v[102:103], v[112:113], v[102:103]
	v_pk_mul_f32 v[72:73], v[72:73], v[162:163] op_sel_hi:[1,0]
	v_pk_mul_f32 v[102:103], v[104:105], v[102:103]
	v_pk_mul_f32 v[74:75], v[74:75], v[162:163] op_sel_hi:[1,0]
	v_cvt_pk_bf16_f32 v99, v102, v103
	v_mul_f32_e32 v102, 0xbfb8aa3b, v106
	v_mul_f32_e32 v103, 0xbfb8aa3b, v107
	v_exp_f32_e32 v102, v102
	v_exp_f32_e32 v103, v103
	v_pk_mul_f32 v[60:61], v[60:61], v[148:149] op_sel_hi:[1,0]
	v_pk_mul_f32 v[52:53], v[52:53], v[148:149] op_sel_hi:[1,0]
	v_add_f32_e32 v102, 1.0, v102
	v_add_f32_e32 v103, 1.0, v103
	v_rcp_f32_e32 v102, v102
	v_rcp_f32_e32 v103, v103
	v_pk_mul_f32 v[62:63], v[62:63], v[148:149] op_sel_hi:[1,0]
	v_pk_mul_f32 v[54:55], v[54:55], v[148:149] op_sel_hi:[1,0]
	v_pk_mul_f32 v[56:57], v[56:57], v[148:149] op_sel_hi:[1,0]
	v_pk_mul_f32 v[102:103], v[106:107], v[102:103]
	v_pk_mul_f32 v[58:59], v[58:59], v[148:149] op_sel_hi:[1,0]
	v_pk_mul_f32 v[100:101], v[100:101], v[102:103]
	v_pk_mul_f32 v[44:45], v[44:45], v[146:147] op_sel_hi:[1,0]
	v_cvt_pk_bf16_f32 v100, v100, v101
	v_mul_f32_e32 v101, 0xbfb8aa3b, v108
	v_exp_f32_e32 v101, v101
	v_pk_mul_f32 v[36:37], v[36:37], v[146:147] op_sel_hi:[1,0]
	v_pk_mul_f32 v[46:47], v[46:47], v[146:147] op_sel_hi:[1,0]
	v_pk_mul_f32 v[38:39], v[38:39], v[146:147] op_sel_hi:[1,0]
	v_add_f32_e32 v101, 1.0, v101
	v_rcp_f32_e32 v102, v101
	v_mul_f32_e32 v101, 0xbfb8aa3b, v109
	v_exp_f32_e32 v101, v101
	v_pk_mul_f32 v[40:41], v[40:41], v[146:147] op_sel_hi:[1,0]
	v_pk_mul_f32 v[42:43], v[42:43], v[146:147] op_sel_hi:[1,0]
	v_pk_mul_f32 v[28:29], v[28:29], v[136:137] op_sel_hi:[1,0]
	v_add_f32_e32 v101, 1.0, v101
	v_rcp_f32_e32 v103, v101
	v_pk_mul_f32 v[20:21], v[20:21], v[136:137] op_sel_hi:[1,0]
	v_pk_mul_f32 v[30:31], v[30:31], v[136:137] op_sel_hi:[1,0]
	v_pk_mul_f32 v[22:23], v[22:23], v[136:137] op_sel_hi:[1,0]
	v_pk_mul_f32 v[102:103], v[108:109], v[102:103]
	v_pk_mul_f32 v[24:25], v[24:25], v[136:137] op_sel_hi:[1,0]
	v_pk_mul_f32 v[102:103], v[116:117], v[102:103]
	v_pk_mul_f32 v[26:27], v[26:27], v[136:137] op_sel_hi:[1,0]
	v_cvt_pk_bf16_f32 v101, v102, v103
	global_store_dwordx4 v[114:115], v[98:101], off
	v_pk_mul_f32 v[12:13], v[12:13], v[130:131] op_sel_hi:[1,0]
	v_pk_mul_f32 v[4:5], v[4:5], v[130:131] op_sel_hi:[1,0]
	v_pk_mul_f32 v[100:101], v[82:83], v[164:165] op_sel_hi:[1,0]
	v_pk_mul_f32 v[82:83], v[80:81], v[164:165] op_sel_hi:[1,0]
	v_mul_f32_e32 v80, 0xbfb8aa3b, v92
	v_mul_f32_e32 v81, 0xbfb8aa3b, v93
	v_exp_f32_e32 v80, v80
	v_exp_f32_e32 v81, v81
	v_or_b32_e32 v98, 32, v210
	v_mad_i64_i32 v[98:99], s[0:1], v98, s2, v[132:133]
	v_add_f32_e32 v80, 1.0, v80
	v_add_f32_e32 v81, 1.0, v81
	v_rcp_f32_e32 v80, v80
	v_rcp_f32_e32 v81, v81
	v_lshl_add_u64 v[98:99], v[98:99], 0, v[134:135]
	v_pk_mul_f32 v[14:15], v[14:15], v[130:131] op_sel_hi:[1,0]
	v_pk_mul_f32 v[6:7], v[6:7], v[130:131] op_sel_hi:[1,0]
	v_pk_mul_f32 v[80:81], v[92:93], v[80:81]
	v_pk_mul_f32 v[8:9], v[8:9], v[130:131] op_sel_hi:[1,0]
	v_pk_mul_f32 v[80:81], v[84:85], v[80:81]
	v_pk_mul_f32 v[10:11], v[10:11], v[130:131] op_sel_hi:[1,0]
	v_cvt_pk_bf16_f32 v80, v80, v81
	v_mul_f32_e32 v81, 0xbfb8aa3b, v94
	v_exp_f32_e32 v81, v81
	s_andn2_b64 vcc, exec, s[38:39]
	v_add_f32_e32 v81, 1.0, v81
	v_rcp_f32_e32 v84, v81
	v_mul_f32_e32 v81, 0xbfb8aa3b, v95
	v_exp_f32_e32 v81, v81
	s_nop 0
	v_add_f32_e32 v81, 1.0, v81
	v_rcp_f32_e32 v85, v81
	s_nop 0
	v_pk_mul_f32 v[84:85], v[94:95], v[84:85]
	s_nop 0
	v_pk_mul_f32 v[84:85], v[86:87], v[84:85]
	s_nop 0
	v_cvt_pk_bf16_f32 v81, v84, v85
	v_mul_f32_e32 v84, 0xbfb8aa3b, v88
	v_mul_f32_e32 v85, 0xbfb8aa3b, v89
	v_exp_f32_e32 v84, v84
	v_exp_f32_e32 v85, v85
	v_add_f32_e32 v84, 1.0, v84
	v_add_f32_e32 v85, 1.0, v85
	v_rcp_f32_e32 v84, v84
	v_rcp_f32_e32 v85, v85
	s_nop 0
	v_pk_mul_f32 v[84:85], v[88:89], v[84:85]
	s_nop 0
	v_pk_mul_f32 v[82:83], v[82:83], v[84:85]
	s_nop 0
	v_cvt_pk_bf16_f32 v82, v82, v83
	v_mul_f32_e32 v83, 0xbfb8aa3b, v90
	v_exp_f32_e32 v83, v83
	s_nop 0
	v_add_f32_e32 v83, 1.0, v83
	v_rcp_f32_e32 v84, v83
	v_mul_f32_e32 v83, 0xbfb8aa3b, v91
	v_exp_f32_e32 v83, v83
	s_nop 0
	v_add_f32_e32 v83, 1.0, v83
	v_rcp_f32_e32 v85, v83
	s_nop 0
	v_pk_mul_f32 v[84:85], v[90:91], v[84:85]
	s_nop 0
	v_pk_mul_f32 v[84:85], v[100:101], v[84:85]
	s_nop 0
	v_cvt_pk_bf16_f32 v83, v84, v85
	global_store_dwordx4 v[98:99], v[80:83], off
	s_nop 1
	v_pk_mul_f32 v[82:83], v[66:67], v[162:163] op_sel_hi:[1,0]
	v_pk_mul_f32 v[66:67], v[64:65], v[162:163] op_sel_hi:[1,0]
	v_mul_f32_e32 v64, 0xbfb8aa3b, v76
	v_mul_f32_e32 v65, 0xbfb8aa3b, v77
	v_exp_f32_e32 v64, v64
	v_exp_f32_e32 v65, v65
	v_or_b32_e32 v80, 48, v210
	v_mad_i64_i32 v[80:81], s[0:1], v80, s2, v[132:133]
	v_add_f32_e32 v64, 1.0, v64
	v_add_f32_e32 v65, 1.0, v65
	v_rcp_f32_e32 v64, v64
	v_rcp_f32_e32 v65, v65
	v_lshl_add_u64 v[80:81], v[80:81], 0, v[134:135]
	v_pk_mul_f32 v[64:65], v[76:77], v[64:65]
	s_nop 0
	v_pk_mul_f32 v[64:65], v[68:69], v[64:65]
	s_nop 0
	v_cvt_pk_bf16_f32 v64, v64, v65
	v_mul_f32_e32 v65, 0xbfb8aa3b, v78
	v_exp_f32_e32 v65, v65
	s_nop 0
	v_add_f32_e32 v65, 1.0, v65
	v_rcp_f32_e32 v68, v65
	v_mul_f32_e32 v65, 0xbfb8aa3b, v79
	v_exp_f32_e32 v65, v65
	s_nop 0
	v_add_f32_e32 v65, 1.0, v65
	v_rcp_f32_e32 v69, v65
	s_nop 0
	v_pk_mul_f32 v[68:69], v[78:79], v[68:69]
	s_nop 0
	v_pk_mul_f32 v[68:69], v[70:71], v[68:69]
	s_nop 0
	v_cvt_pk_bf16_f32 v65, v68, v69
; __device__ __forceinline__ unsigned pk_bf16(float lo, float hi) { f32x2e v = {lo, hi}; bf16x2e b = __builtin_convertvector(v, bf16x2e); return __builtin_bit_cast(unsigned, b); }
; __device__ __forceinline__ float silu_mul(float g, float u) { return g * __builtin_amdgcn_rcpf(1.0f + __builtin_amdgcn_exp2f(-1.4426950408889634f * g)) * u; }
;     __device__ __forceinline__ void operator()(const f32x4 (&acc)[2][2][4][2], const Unit& u, int wr, int wc, int fr, int fq) const {
;     ...
;             for (int m = 0; m < 4; ++m) { bf16_t* rowp = O + (size_t)(row0 + ai * HALF + m * 16) * ldc + col0;
;                 const float rs = rsa[ai][m];
;                 const f32x4 g0 = acc[ai][0][m][0] * rs, g1 = acc[ai][0][m][1] * rs, u0 = acc[ai][1][m][0] * rs, u1 = acc[ai][1][m][1] * rs;
;                 u32x4 w; w.x = pk_bf16(silu_mul(g0[0], u0[0]), silu_mul(g0[1], u0[1])); w.y = pk_bf16(silu_mul(g0[2], u0[2]), silu_mul(g0[3], u0[3]));
;                 w.z = pk_bf16(silu_mul(g1[0], u1[0]), silu_mul(g1[1], u1[1])); w.w = pk_bf16(silu_mul(g1[2], u1[2]), silu_mul(g1[3], u1[3]));
;                 *(u32x4*)rowp = w; }
	v_mul_f32_e32 v68, 0xbfb8aa3b, v72
	v_mul_f32_e32 v69, 0xbfb8aa3b, v73
	v_exp_f32_e32 v68, v68
	v_exp_f32_e32 v69, v69
	v_add_f32_e32 v68, 1.0, v68
	v_add_f32_e32 v69, 1.0, v69
	v_rcp_f32_e32 v68, v68
	v_rcp_f32_e32 v69, v69
	s_nop 0
	v_pk_mul_f32 v[68:69], v[72:73], v[68:69]
	s_nop 0
	v_pk_mul_f32 v[66:67], v[66:67], v[68:69]
	s_nop 0
	v_cvt_pk_bf16_f32 v66, v66, v67
	v_mul_f32_e32 v67, 0xbfb8aa3b, v74
	v_exp_f32_e32 v67, v67
	s_nop 0
	v_add_f32_e32 v67, 1.0, v67
	v_rcp_f32_e32 v68, v67
	v_mul_f32_e32 v67, 0xbfb8aa3b, v75
	v_exp_f32_e32 v67, v67
	s_nop 0
	v_add_f32_e32 v67, 1.0, v67
	v_rcp_f32_e32 v69, v67
	s_nop 0
	v_pk_mul_f32 v[68:69], v[74:75], v[68:69]
	s_nop 0
	v_pk_mul_f32 v[68:69], v[82:83], v[68:69]
	s_nop 0
	v_cvt_pk_bf16_f32 v67, v68, v69
	global_store_dwordx4 v[80:81], v[64:67], off
	s_nop 1
	v_pk_mul_f32 v[66:67], v[50:51], v[148:149] op_sel_hi:[1,0]
	v_pk_mul_f32 v[50:51], v[48:49], v[148:149] op_sel_hi:[1,0]
	v_mul_f32_e32 v48, 0xbfb8aa3b, v60
	v_mul_f32_e32 v49, 0xbfb8aa3b, v61
	v_exp_f32_e32 v48, v48
	v_exp_f32_e32 v49, v49
	v_add_u32_e32 v64, 0x80, v210
	v_mad_i64_i32 v[64:65], s[0:1], v64, s2, v[132:133]
	v_add_f32_e32 v48, 1.0, v48
	v_add_f32_e32 v49, 1.0, v49
	v_rcp_f32_e32 v48, v48
	v_rcp_f32_e32 v49, v49
	v_lshl_add_u64 v[64:65], v[64:65], 0, v[134:135]
	v_pk_mul_f32 v[48:49], v[60:61], v[48:49]
	s_nop 0
	v_pk_mul_f32 v[48:49], v[52:53], v[48:49]
	s_nop 0
	v_cvt_pk_bf16_f32 v48, v48, v49
	v_mul_f32_e32 v49, 0xbfb8aa3b, v62
	v_exp_f32_e32 v49, v49
	s_nop 0
	v_add_f32_e32 v49, 1.0, v49
	v_rcp_f32_e32 v52, v49
	v_mul_f32_e32 v49, 0xbfb8aa3b, v63
	v_exp_f32_e32 v49, v49
	s_nop 0
	v_add_f32_e32 v49, 1.0, v49
	v_rcp_f32_e32 v53, v49
	s_nop 0
	v_pk_mul_f32 v[52:53], v[62:63], v[52:53]
	s_nop 0
	v_pk_mul_f32 v[52:53], v[54:55], v[52:53]
	s_nop 0
	v_cvt_pk_bf16_f32 v49, v52, v53
	v_mul_f32_e32 v52, 0xbfb8aa3b, v56
	v_mul_f32_e32 v53, 0xbfb8aa3b, v57
	v_exp_f32_e32 v52, v52
	v_exp_f32_e32 v53, v53
	v_add_f32_e32 v52, 1.0, v52
	v_add_f32_e32 v53, 1.0, v53
	v_rcp_f32_e32 v52, v52
	v_rcp_f32_e32 v53, v53
	s_nop 0
	v_pk_mul_f32 v[52:53], v[56:57], v[52:53]
	s_nop 0
	v_pk_mul_f32 v[50:51], v[50:51], v[52:53]
	s_nop 0
	v_cvt_pk_bf16_f32 v50, v50, v51
	v_mul_f32_e32 v51, 0xbfb8aa3b, v58
	v_exp_f32_e32 v51, v51
	s_nop 0
	v_add_f32_e32 v51, 1.0, v51
	v_rcp_f32_e32 v52, v51
	v_mul_f32_e32 v51, 0xbfb8aa3b, v59
	v_exp_f32_e32 v51, v51
	s_nop 0
	v_add_f32_e32 v51, 1.0, v51
	v_rcp_f32_e32 v53, v51
	s_nop 0
	v_pk_mul_f32 v[52:53], v[58:59], v[52:53]
	s_nop 0
	v_pk_mul_f32 v[52:53], v[66:67], v[52:53]
	s_nop 0
	v_cvt_pk_bf16_f32 v51, v52, v53
	global_store_dwordx4 v[64:65], v[48:51], off
	s_nop 1
	v_pk_mul_f32 v[50:51], v[34:35], v[146:147] op_sel_hi:[1,0]
	v_pk_mul_f32 v[34:35], v[32:33], v[146:147] op_sel_hi:[1,0]
	v_mul_f32_e32 v32, 0xbfb8aa3b, v44
	v_mul_f32_e32 v33, 0xbfb8aa3b, v45
	v_exp_f32_e32 v32, v32
	v_exp_f32_e32 v33, v33
	v_add_u32_e32 v48, 0x90, v210
	v_mad_i64_i32 v[48:49], s[0:1], v48, s2, v[132:133]
	v_add_f32_e32 v32, 1.0, v32
	v_add_f32_e32 v33, 1.0, v33
	v_rcp_f32_e32 v32, v32
	v_rcp_f32_e32 v33, v33
	v_lshl_add_u64 v[48:49], v[48:49], 0, v[134:135]
	v_pk_mul_f32 v[32:33], v[44:45], v[32:33]
	s_nop 0
	v_pk_mul_f32 v[32:33], v[36:37], v[32:33]
	s_nop 0
	v_cvt_pk_bf16_f32 v32, v32, v33
	v_mul_f32_e32 v33, 0xbfb8aa3b, v46
	v_exp_f32_e32 v33, v33
	s_nop 0
	v_add_f32_e32 v33, 1.0, v33
	v_rcp_f32_e32 v36, v33
	v_mul_f32_e32 v33, 0xbfb8aa3b, v47
	v_exp_f32_e32 v33, v33
	s_nop 0
	v_add_f32_e32 v33, 1.0, v33
	v_rcp_f32_e32 v37, v33
	s_nop 0
	v_pk_mul_f32 v[36:37], v[46:47], v[36:37]
	s_nop 0
	v_pk_mul_f32 v[36:37], v[38:39], v[36:37]
	s_nop 0
	v_cvt_pk_bf16_f32 v33, v36, v37
	v_mul_f32_e32 v36, 0xbfb8aa3b, v40
	v_mul_f32_e32 v37, 0xbfb8aa3b, v41
	v_exp_f32_e32 v36, v36
	v_exp_f32_e32 v37, v37
	v_add_f32_e32 v36, 1.0, v36
	v_add_f32_e32 v37, 1.0, v37
	v_rcp_f32_e32 v36, v36
	v_rcp_f32_e32 v37, v37
	s_nop 0
	v_pk_mul_f32 v[36:37], v[40:41], v[36:37]
	s_nop 0
	v_pk_mul_f32 v[34:35], v[34:35], v[36:37]
	s_nop 0
	v_cvt_pk_bf16_f32 v34, v34, v35
; __device__ __forceinline__ unsigned pk_bf16(float lo, float hi) { f32x2e v = {lo, hi}; bf16x2e b = __builtin_convertvector(v, bf16x2e); return __builtin_bit_cast(unsigned, b); }
; __device__ __forceinline__ float silu_mul(float g, float u) { return g * __builtin_amdgcn_rcpf(1.0f + __builtin_amdgcn_exp2f(-1.4426950408889634f * g)) * u; }
;     __device__ __forceinline__ void operator()(const f32x4 (&acc)[2][2][4][2], const Unit& u, int wr, int wc, int fr, int fq) const {
;     ...
;             for (int m = 0; m < 4; ++m) { bf16_t* rowp = O + (size_t)(row0 + ai * HALF + m * 16) * ldc + col0;
;                 const float rs = rsa[ai][m];
;                 const f32x4 g0 = acc[ai][0][m][0] * rs, g1 = acc[ai][0][m][1] * rs, u0 = acc[ai][1][m][0] * rs, u1 = acc[ai][1][m][1] * rs;
;                 u32x4 w; w.x = pk_bf16(silu_mul(g0[0], u0[0]), silu_mul(g0[1], u0[1])); w.y = pk_bf16(silu_mul(g0[2], u0[2]), silu_mul(g0[3], u0[3]));
;                 w.z = pk_bf16(silu_mul(g1[0], u1[0]), silu_mul(g1[1], u1[1])); w.w = pk_bf16(silu_mul(g1[2], u1[2]), silu_mul(g1[3], u1[3]));
;                 *(u32x4*)rowp = w; }
	v_mul_f32_e32 v35, 0xbfb8aa3b, v42
	v_exp_f32_e32 v35, v35
	s_nop 0
	v_add_f32_e32 v35, 1.0, v35
	v_rcp_f32_e32 v36, v35
	v_mul_f32_e32 v35, 0xbfb8aa3b, v43
	v_exp_f32_e32 v35, v35
	s_nop 0
	v_add_f32_e32 v35, 1.0, v35
	v_rcp_f32_e32 v37, v35
	s_nop 0
	v_pk_mul_f32 v[36:37], v[42:43], v[36:37]
	s_nop 0
	v_pk_mul_f32 v[36:37], v[50:51], v[36:37]
	s_nop 0
	v_cvt_pk_bf16_f32 v35, v36, v37
	global_store_dwordx4 v[48:49], v[32:35], off
	s_nop 1
	v_pk_mul_f32 v[34:35], v[18:19], v[136:137] op_sel_hi:[1,0]
	v_pk_mul_f32 v[18:19], v[16:17], v[136:137] op_sel_hi:[1,0]
	v_mul_f32_e32 v16, 0xbfb8aa3b, v28
	v_mul_f32_e32 v17, 0xbfb8aa3b, v29
	v_exp_f32_e32 v16, v16
	v_exp_f32_e32 v17, v17
	v_add_u32_e32 v32, 0xa0, v210
	v_mad_i64_i32 v[32:33], s[0:1], v32, s2, v[132:133]
	v_add_f32_e32 v16, 1.0, v16
	v_add_f32_e32 v17, 1.0, v17
	v_rcp_f32_e32 v16, v16
	v_rcp_f32_e32 v17, v17
	v_lshl_add_u64 v[32:33], v[32:33], 0, v[134:135]
	v_pk_mul_f32 v[16:17], v[28:29], v[16:17]
	s_nop 0
	v_pk_mul_f32 v[16:17], v[20:21], v[16:17]
	s_nop 0
	v_cvt_pk_bf16_f32 v16, v16, v17
	v_mul_f32_e32 v17, 0xbfb8aa3b, v30
	v_exp_f32_e32 v17, v17
	s_nop 0
	v_add_f32_e32 v17, 1.0, v17
	v_rcp_f32_e32 v20, v17
	v_mul_f32_e32 v17, 0xbfb8aa3b, v31
	v_exp_f32_e32 v17, v17
	s_nop 0
	v_add_f32_e32 v17, 1.0, v17
	v_rcp_f32_e32 v21, v17
	s_nop 0
	v_pk_mul_f32 v[20:21], v[30:31], v[20:21]
	s_nop 0
	v_pk_mul_f32 v[20:21], v[22:23], v[20:21]
	s_nop 0
	v_cvt_pk_bf16_f32 v17, v20, v21
	v_mul_f32_e32 v20, 0xbfb8aa3b, v24
	v_mul_f32_e32 v21, 0xbfb8aa3b, v25
	v_exp_f32_e32 v20, v20
	v_exp_f32_e32 v21, v21
	v_add_f32_e32 v20, 1.0, v20
	v_add_f32_e32 v21, 1.0, v21
	v_rcp_f32_e32 v20, v20
	v_rcp_f32_e32 v21, v21
	s_nop 0
	v_pk_mul_f32 v[20:21], v[24:25], v[20:21]
	s_nop 0
	v_pk_mul_f32 v[18:19], v[18:19], v[20:21]
	s_nop 0
	v_cvt_pk_bf16_f32 v18, v18, v19
	v_mul_f32_e32 v19, 0xbfb8aa3b, v26
	v_exp_f32_e32 v19, v19
	s_nop 0
	v_add_f32_e32 v19, 1.0, v19
	v_rcp_f32_e32 v20, v19
	v_mul_f32_e32 v19, 0xbfb8aa3b, v27
	v_exp_f32_e32 v19, v19
	s_nop 0
	v_add_f32_e32 v19, 1.0, v19
	v_rcp_f32_e32 v21, v19
	s_nop 0
	v_pk_mul_f32 v[20:21], v[26:27], v[20:21]
	s_nop 0
	v_pk_mul_f32 v[20:21], v[34:35], v[20:21]
	s_nop 0
	v_cvt_pk_bf16_f32 v19, v20, v21
	global_store_dwordx4 v[32:33], v[16:19], off
	s_nop 1
	v_pk_mul_f32 v[18:19], v[2:3], v[130:131] op_sel_hi:[1,0]
	v_pk_mul_f32 v[2:3], v[0:1], v[130:131] op_sel_hi:[1,0]
	v_mul_f32_e32 v0, 0xbfb8aa3b, v12
	v_mul_f32_e32 v1, 0xbfb8aa3b, v13
	v_exp_f32_e32 v0, v0
	v_exp_f32_e32 v1, v1
	v_add_u32_e32 v16, 0xb0, v210
	v_mad_i64_i32 v[16:17], s[0:1], v16, s2, v[132:133]
	v_add_f32_e32 v0, 1.0, v0
	v_add_f32_e32 v1, 1.0, v1
	v_rcp_f32_e32 v0, v0
	v_rcp_f32_e32 v1, v1
	v_lshl_add_u64 v[16:17], v[16:17], 0, v[134:135]
	s_mov_b64 s[0:1], -1
	v_pk_mul_f32 v[0:1], v[12:13], v[0:1]
	s_nop 0
	v_pk_mul_f32 v[0:1], v[4:5], v[0:1]
	s_nop 0
	v_cvt_pk_bf16_f32 v0, v0, v1
	v_mul_f32_e32 v1, 0xbfb8aa3b, v14
	v_exp_f32_e32 v1, v1
	s_nop 0
	v_add_f32_e32 v1, 1.0, v1
	v_rcp_f32_e32 v4, v1
	v_mul_f32_e32 v1, 0xbfb8aa3b, v15
	v_exp_f32_e32 v1, v1
	s_nop 0
	v_add_f32_e32 v1, 1.0, v1
	v_rcp_f32_e32 v5, v1
	s_nop 0
	v_pk_mul_f32 v[4:5], v[14:15], v[4:5]
	s_nop 0
	v_pk_mul_f32 v[4:5], v[6:7], v[4:5]
	s_nop 0
	v_cvt_pk_bf16_f32 v1, v4, v5
	v_mul_f32_e32 v4, 0xbfb8aa3b, v8
	v_mul_f32_e32 v5, 0xbfb8aa3b, v9
	v_exp_f32_e32 v4, v4
	v_exp_f32_e32 v5, v5
	v_add_f32_e32 v4, 1.0, v4
	v_add_f32_e32 v5, 1.0, v5
	v_rcp_f32_e32 v4, v4
	v_rcp_f32_e32 v5, v5
	s_nop 0
	v_pk_mul_f32 v[4:5], v[8:9], v[4:5]
	s_nop 0
	v_pk_mul_f32 v[2:3], v[2:3], v[4:5]
	s_nop 0
	v_cvt_pk_bf16_f32 v2, v2, v3
	v_mul_f32_e32 v3, 0xbfb8aa3b, v10
	v_exp_f32_e32 v3, v3
	s_nop 0
	v_add_f32_e32 v3, 1.0, v3
	v_rcp_f32_e32 v4, v3
	v_mul_f32_e32 v3, 0xbfb8aa3b, v11
	v_exp_f32_e32 v3, v3
	s_nop 0
	v_add_f32_e32 v3, 1.0, v3
	v_rcp_f32_e32 v5, v3
	s_nop 0
	v_pk_mul_f32 v[4:5], v[10:11], v[4:5]
	s_nop 0
	v_pk_mul_f32 v[4:5], v[18:19], v[4:5]
	s_nop 0
	v_cvt_pk_bf16_f32 v3, v4, v5
	global_store_dwordx4 v[16:17], v[0:3], off
	s_branch .Lswi_join
